# FoX work items reordered head-major (all query tiles of one batch-head are consecutive in the queue) so concurrently running blocks share K/V tiles in cache
# speedup vs baseline: 1.0117x; 1.0083x over previous
.LBB0_307:
	s_mul_hi_u32 s7, s2, 0x3f03f04
	s_mul_i32 s1, s7, 0x41
	v_mov_b32_e32 v104, v177
	s_sub_i32 s3, s2, s1
	s_nop 0
	v_ashrrev_i32_e32 v4, 6, v104
	s_nop 0
	v_readfirstlane_b32 s0, v4
	s_sub_i32 s6, 64, s3
	s_nop 0
	s_mov_b64 s[68:69], s[50:51]
	s_ashr_i32 s50, s7, 3
	s_lshl_b32 s18, s6, 7
	s_lshl_b32 s0, s0, 5
	s_add_i32 s52, s0, s18
	s_mul_i32 s0, s50, 0x2ce0c00
	s_ashr_i32 s1, s0, 31
	s_lshl_b64 s[0:1], s[0:1], 1
	s_add_u32 s2, s56, s0
	v_and_b32_e32 v5, 31, v104
	s_addc_u32 s3, s57, s1
	v_or_b32_e32 v102, s52, v5
	v_mov_b64_e32 v[0:1], s[2:3]
	v_mad_i64_i32 v[0:1], s[0:1], v102, s13, v[0:1]
	s_lshl_b32 s0, s7, 6
	s_and_b32 s0, s0, 0x1c0
	v_bfe_u32 v3, v104, 5, 1
	s_lshl_b32 s92, s0, 1
	s_mov_b32 s93, s17
	v_readlane_b32 s8, v245, 36
	v_lshl_add_u64 v[0:1], v[0:1], 0, s[92:93]
	v_lshlrev_b32_e32 v178, 4, v3
	s_mul_i32 s1, s7, 0x410
	v_readlane_b32 s10, v245, 38
	v_and_b32_e32 v2, 63, v104
	v_lshl_add_u64 v[0:1], v[0:1], 0, v[178:179]
	s_mul_hi_i32 s0, s7, 0x410
	v_readlane_b32 s11, v245, 39
	s_add_u32 s10, s10, s1
	global_load_dwordx4 v[64:67], v[0:1], off
	global_load_dwordx4 v[68:71], v[0:1], off offset:32
	global_load_dwordx4 v[72:75], v[0:1], off offset:64
	global_load_dwordx4 v[76:79], v[0:1], off offset:96
	s_addc_u32 s11, s11, s0
	v_lshlrev_b32_e32 v0, 3, v2
	global_load_dword v1, v0, s[10:11] offset:4
	s_nop 0
	global_load_dword v0, v0, s[10:11] offset:516
	s_movk_i32 s0, 0x82
	v_readlane_b32 s9, v245, 37
	s_waitcnt vmcnt(0)
	v_max3_f32 v0, v1, 0, v0
	v_or_b32_e32 v1, 0x80, v2
	v_cmp_gt_u32_e32 vcc, s0, v1
	s_and_saveexec_b64 s[0:1], vcc
	s_cbranch_execz .LBB0_309
	v_lshlrev_b32_e32 v1, 3, v1
	global_load_dword v1, v1, s[10:11] offset:4
	v_max_f32_e32 v0, v0, v0
	s_waitcnt vmcnt(0)
	v_max_f32_e32 v1, v1, v1
	v_max_f32_e32 v0, v0, v1
